# GDN KK/QK tiles: all LDS fragment + gate reads issued up front with counted waits
# speedup vs baseline: 1.0518x; 1.0002x over previous
.Lgpf_skip:
	v_mad_u64_u32 v[116:117], s[10:11], v108, s71, v[0:1]
	v_or_b32_e32 v119, s93, v206
	v_mul_lo_u32 v112, v119, s71
	v_add3_u32 v117, s91, v112, v118
	ds_read_b128 v[228:231], v116 offset:17408
	ds_read_b128 v[232:235], v117
	ds_read_b128 v[236:239], v116 offset:17472
	ds_read_b128 v[240:243], v117 offset:64
	ds_read_b128 v[244:247], v116 offset:17536
	ds_read_b128 v[248:251], v117 offset:128
	ds_read_b128 v[252:255], v116 offset:17600
	ds_read_b128 v[128:131], v117 offset:192
	v_lshrrev_b32_e32 v207, 4, v3
	s_mov_b64 s[12:13], -1
	v_add_u32_e32 v117, s81, v118
	v_lshlrev_b32_e32 v116, 2, v207
	v_lshlrev_b32_e32 v108, 2, v119
	v_add_u32_e32 v109, s81, v108
	v_add_u32_e32 v108, s82, v108
	v_lshl_add_u32 v110, s92, 2, v117
	ds_read_b32 v121, v109
	ds_read_b32 v118, v108
	ds_read_b128 v[108:111], v110
	v_cndmask_b32_e64 v122, 0, 1, s[18:19]
	v_or_b32_e32 v120, s92, v116
	v_cmp_ne_u32_e64 s[10:11], 1, v122
	s_waitcnt lgkmcnt(9)
	v_mfma_f32_16x16x32_bf16 v[112:115], v[228:231], v[232:235], 0
	s_waitcnt lgkmcnt(7)
	v_mfma_f32_16x16x32_bf16 v[112:115], v[236:239], v[240:243], v[112:115]
	s_waitcnt lgkmcnt(5)
	v_mfma_f32_16x16x32_bf16 v[112:115], v[244:247], v[248:251], v[112:115]
	s_waitcnt lgkmcnt(3)
	v_mfma_f32_16x16x32_bf16 v[112:115], v[252:255], v[128:131], v[112:115]
	s_nop 3
	s_andn2_b64 vcc, exec, s[18:19]
	s_waitcnt lgkmcnt(0)
	v_sub_f32_e32 v108, v121, v108
	v_mul_f32_e32 v122, 0x3fb8aa3b, v108
	s_cbranch_vccnz .LBB0_363
	v_exp_f32_e32 v108, v122
	v_cmp_le_i32_e32 vcc, v120, v119
	s_mov_b64 s[12:13], 0
	v_mul_f32_e32 v108, v112, v108
	v_cndmask_b32_e32 v108, 0, v108, vcc

.LBB0_387:
	s_lshr_b32 s13, s38, 1
	s_sub_i32 s13, s51, s13
	s_lshl_b32 s27, s13, 4
	v_or_b32_e32 v108, s27, v206
	v_lshl_or_b32 v119, s50, 4, v206
	v_mad_u64_u32 v[124:125], s[38:39], v108, s71, v[0:1]
	v_mul_i32_i24_e32 v108, 0x110, v119
	v_lshlrev_b32_e32 v109, 1, v208
	v_add3_u32 v125, s12, v108, v109
	ds_read_b128 v[228:231], v124 offset:17408
	ds_read_b128 v[232:235], v125
	ds_read_b128 v[236:239], v124 offset:17472
	ds_read_b128 v[240:243], v125 offset:64
	ds_read_b128 v[244:247], v124 offset:17536
	ds_read_b128 v[248:251], v125 offset:128
	ds_read_b128 v[252:255], v124 offset:17600
	ds_read_b128 v[128:131], v125 offset:192
	v_lshlrev_b32_e32 v112, 2, v119
	v_add_u32_e32 v113, s81, v112
	v_add_u32_e32 v112, s82, v112
	ds_read_b32 v120, v113
	ds_read_b32 v121, v112
	v_lshl_add_u32 v112, s13, 6, v117
	ds_read_b128 v[112:115], v112
	s_and_b64 vcc, exec, s[48:49]
	s_waitcnt lgkmcnt(9)
	v_mfma_f32_16x16x32_bf16 v[108:111], v[228:231], v[232:235], 0
	s_waitcnt lgkmcnt(7)
	v_mfma_f32_16x16x32_bf16 v[108:111], v[236:239], v[240:243], v[108:111]
	s_waitcnt lgkmcnt(5)
	v_mfma_f32_16x16x32_bf16 v[108:111], v[244:247], v[248:251], v[108:111]
	s_waitcnt lgkmcnt(3)
	v_mfma_f32_16x16x32_bf16 v[108:111], v[252:255], v[128:131], v[108:111]
	s_nop 3
	v_or_b32_e32 v122, s27, v116
	s_mov_b64 s[12:13], -1
	s_waitcnt lgkmcnt(0)
	v_sub_f32_e32 v112, v120, v112
	v_mul_f32_e32 v123, 0x3fb8aa3b, v112
	s_cbranch_vccz .LBB0_389
	v_exp_f32_e32 v112, v123
	v_cmp_le_i32_e32 vcc, v122, v119
	s_mov_b64 s[12:13], 0
	v_mul_f32_e32 v112, v108, v112
	v_cndmask_b32_e32 v112, 0, v112, vcc
